# in-projection epilogue: next unit's per-row 1/rms values prefetched into LDS by LDS-DMA during the current epilogue (double-buffered); no per-unit global-load round trip
# speedup vs baseline: 1.0055x; 1.0001x over previous
;     __device__ bool next(int i, Unit& u) const { const long L = (long)i * G + c; if (L >= 128) return false; u.pm = (int)L & 31; u.pn = u.pm >> 4; u.koff = ((int)L >> 5) * 1024; return true; }
;     __host__ __device__ bool next(int i, Unit& u) const {
;         const long L = (long)i * G + c; if (L >= nwg) return false;
;         int wgid = (int)L; { const int q = nwg / NXCD, r = nwg % NXCD, xcd = wgid % NXCD, off = wgid / NXCD; wgid = (xcd < r ? xcd * (q + 1) : r * (q + 1) + (xcd - r) * q) + off; }
;         const int nig = WGM * nN, gid = wgid / nig, fm = gid * WGM, gsz = (nM - fm) < WGM ? (nM - fm) : WGM;
;         u.pm = fm + ((wgid % nig) % gsz); u.pn = (wgid % nig) / gsz; u.koff = 0; return true;
; __global__ void __launch_bounds__(NWAVES * 64, 2) fwd_kernel(Args args) {
;     ...
;     if (IN(1)) {
;         pg8::Gemm g{(const bf16_t*)(ws + WS_XB), (const bf16_t*)(ws + WS_WIN), T, NIN, DM, DM, DM};
;         pg8::StaticOrder So; So.init(T, NIN, G, (int)blockIdx.x);
;         EpiInProj E{(const float*)(ws + WS_RINV1), args.in[3], args.in[4], args.in[8], (const float*)(ws + WS_ROPEC), (const float*)(ws + WS_ROPES),
;                     (bf16_t*)(ws + WS_QN), (bf16_t*)(ws + WS_QR), (bf16_t*)(ws + WS_KC), (bf16_t*)(ws + WS_VC), (bf16_t*)(ws + WS_KSL), (bf16_t*)(ws + WS_VSLT),
;                     (bf16_t*)(ws + WS_KWN), (bf16_t*)(ws + WS_VWNT), (bf16_t*)(ws + WS_ZU), (bf16_t*)(ws + WS_ZVT), (float*)(ws + WS_GATES)};
;         pg8::gemm_phase<EpiInProj, pg8::StaticOrder, true, true>(lds, g, So, E);
.LBB0_145:
	s_mov_b32 s98, 0
	s_mov_b32 s99, 0
	v_readlane_b32 s0, v254, 0
	v_readlane_b32 s1, v254, 1
	s_cmp_lt_i32 s0, 2
	s_cselect_b64 s[0:1], -1, 0
	s_and_b64 s[10:11], s[0:1], s[72:73]
	s_andn2_b64 vcc, exec, s[10:11]
	s_cbranch_vccnz .LBB0_429
	s_cmpk_lt_i32 s70, 0x500
	s_cselect_b64 s[2:3], -1, 0
	s_cmpk_gt_i32 s70, 0x4ff
	v_readfirstlane_b32 s4, v184
	s_cbranch_scc1 .LBB0_148
	s_ashr_i32 s5, s70, 31
	s_lshr_b32 s5, s5, 29
	s_add_i32 s5, s70, s5
	s_ashr_i32 s6, s5, 3
	s_and_b32 s5, s5, -8
	s_sub_i32 s5, s70, s5
	s_cmp_lt_i32 s5, 0
	s_movk_i32 s7, 0xa1
	s_cselect_b32 s7, s7, 0xa0
	s_mul_i32 s5, s5, s7
	s_add_i32 s5, s5, s6
	s_mul_hi_i32 s6, s5, 0x66666667
	s_lshr_b32 s7, s6, 31
	s_ashr_i32 s6, s6, 4
	s_add_i32 s6, s6, s7
	s_lshl_b32 s7, s6, 2
	s_mul_i32 s6, s6, 40
	s_sub_i32 s5, s5, s6
	s_bfe_i32 s6, s5, 0x80000
	s_bfe_u32 s6, s6, 0x2000d
	s_add_i32 s6, s5, s6
	s_bfe_i32 s8, s6, 0x80000
	s_and_b32 s6, s6, 0xfc
	s_sub_i32 s5, s5, s6
	s_sext_i32_i16 s8, s8
	s_sext_i32_i8 s5, s5
	s_add_i32 s6, s7, s5
	s_ashr_i32 s8, s8, 2

;     __device__ __forceinline__ void operator()(const f32x4 (&acc)[2][2][4][2], const pg8::Unit& u, int wr, int wc, int fr, int fq) const {
;         const int cs = u.pn * 4 + wc;
;         if (cs >= 37) return;
;         const int d0 = 8 * fq;
;         float rsv[2][4];
; #pragma unroll
;         for (int ai = 0; ai < 2; ++ai)
; #pragma unroll
;             for (int m = 0; m < 4; ++m) rsv[ai][m] = rinv1[u.pm * 256 + ai * 128 + wr * 64 + m * 16 + fr];
; #pragma unroll
;         for (int ai = 0; ai < 2; ++ai)
; #pragma unroll
;             for (int m = 0; m < 4; ++m) {
;                 const int row = u.pm * 256 + ai * 128 + wr * 64 + m * 16 + fr;
;                 const float rs = rsv[ai][m];
;                 float v[16];
; #pragma unroll
;                 for (int bj = 0; bj < 2; ++bj)
; #pragma unroll
;                     for (int n = 0; n < 2; ++n)
; #pragma unroll
;                         for (int e = 0; e < 4; ++e) v[bj * 8 + n * 4 + e] = acc[ai][bj][m][n][e] * rs;
;                 const int b = row >> 11, s = row & 2047;
;                 if (cs < 8 || cs == 12 || cs == 13 || cs == 16 || cs == 17) {
;                     const float* gg = cs < 8 ? g_q : (cs < 14 ? g_k + 64 : g_k + 128);
;                     const float rn = rsqrtf(head_ssq(v) * (1.f / 64.f) + EPS) * (cs < 8 ? QSCALE : 1.f);
.LBB0_160:
	s_add_i32 s99, s99, 1
	s_xor_b32 s98, s98, 0x400
	s_cmp_lg_u64 s[4:5], 0
	s_cbranch_scc0 .Lr1_nodma
	v_readfirstlane_b32 s7, v184
	s_lshr_b32 s7, s7, 6
	s_cmp_gt_u32 s7, 3
	s_cbranch_scc1 .Lr1_nodma
	s_lshl_b32 s10, s28, 8
	s_lshl_b32 s11, s7, 6
	s_add_i32 s10, s10, s11
	v_and_b32_e32 v166, 63, v184
	v_add_u32_e32 v166, s10, v166
	v_lshlrev_b32_e32 v166, 2, v166
	s_lshl_b32 s7, s7, 8
	s_add_i32 s7, s7, s98
	s_add_i32 m0, s7, 0x20000
	s_nop 1
	global_load_lds_dword v166, s[12:13]
.Lr1_nodma:
	s_lshl_b32 s7, s8, 2
	s_or_b32 s88, s7, s85
	s_cmp_gt_i32 s88, 36
	s_cbranch_scc1 .LBB0_425
	s_lshl_b32 s89, s6, 8
	v_or_b32_e32 v136, s92, v138
	s_cmp_eq_u32 s99, 1
	s_cbranch_scc1 .Lr1_glob
	s_xor_b32 s29, s98, 0x400
	v_lshlrev_b32_e32 v167, 2, v136
	v_add_u32_e32 v167, s29, v167
	v_add_u32_e32 v167, 0x20000, v167
	ds_read_b32 v198, v167 offset:64
	ds_read_b32 v196, v167 offset:128
	ds_read_b32 v194, v167 offset:192
	ds_read_b32 v192, v167 offset:512
	ds_read_b32 v190, v167 offset:576
	ds_read_b32 v188, v167 offset:640
	ds_read_b32 v186, v167 offset:704
	ds_read_b32 v136, v167
	s_waitcnt lgkmcnt(0)
	s_branch .Lr1_join
.Lr1_glob:
	v_add_u32_e32 v166, s89, v136
	v_ashrrev_i32_e32 v167, 31, v166
	v_lshl_add_u64 v[168:169], v[166:167], 2, s[12:13]
	global_load_dword v136, v[168:169], off
	global_load_dword v198, v[168:169], off offset:64
	global_load_dword v196, v[168:169], off offset:128
	global_load_dword v194, v[168:169], off offset:192
	v_add_u32_e32 v168, 0x80, v166
	v_ashrrev_i32_e32 v169, 31, v168
	v_lshl_add_u64 v[168:169], v[168:169], 2, s[12:13]
	global_load_dword v192, v[168:169], off
	v_add_u32_e32 v168, 0x90, v166
	v_ashrrev_i32_e32 v169, 31, v168
	v_lshl_add_u64 v[168:169], v[168:169], 2, s[12:13]
	global_load_dword v190, v[168:169], off
	v_add_u32_e32 v168, 0xa0, v166
	v_add_u32_e32 v166, 0xb0, v166
	v_ashrrev_i32_e32 v169, 31, v168
	v_ashrrev_i32_e32 v167, 31, v166
	v_lshl_add_u64 v[168:169], v[168:169], 2, s[12:13]
	v_lshl_add_u64 v[166:167], v[166:167], 2, s[12:13]
	global_load_dword v188, v[168:169], off
	global_load_dword v186, v[166:167], off
	s_waitcnt vmcnt(0)
.Lr1_join:
	s_cmp_gt_i32 s88, 7
	s_cselect_b64 s[54:55], -1, 0
	s_cmp_lt_u32 s88, 14
	s_cselect_b64 s[10:11], -1, 0
	s_cmp_gt_i32 s88, 11
	s_cselect_b64 s[72:73], -1, 0
	s_cmp_gt_u32 s7, 19
	s_cselect_b64 s[70:71], -1, 0
	s_cmp_gt_u32 s7, 27
	s_cselect_b64 s[42:43], -1, 0
	s_cmp_lg_u32 s88, 36
	s_cselect_b64 s[40:41], -1, 0
	s_sub_i32 s29, s88, 28
	s_lshl_b32 s27, s29, 6
	s_lshl_b32 s94, s88, 6
	s_cmp_lt_u32 s7, 16
	s_cselect_b64 s[38:39], -1, 0
	s_cmp_lt_i32 s88, 10
	s_cselect_b64 s[68:69], -1, 0
	s_add_i32 s89, s89, s92
	s_ashr_i32 s52, s89, 11
	s_cmp_lt_i32 s88, 8
	s_mov_b32 s8, s94
	v_bitop3_b32 v169, s89, v163, v138 bitop3:0xc8
	v_mul_f32_e32 v171, v124, v136
	v_mul_f32_e32 v173, v125, v136
	v_mul_f32_e32 v175, v126, v136
	v_mul_f32_e32 v185, v127, v136
	v_mul_f32_e32 v187, v120, v136
	v_mul_f32_e32 v189, v121, v136
	v_mul_f32_e32 v191, v122, v136
	v_mul_f32_e32 v193, v123, v136
	v_pk_mul_f32 v[200:201], v[116:117], v[136:137] op_sel_hi:[1,0]
	v_pk_mul_f32 v[126:127], v[118:119], v[136:137] op_sel_hi:[1,0]
	v_pk_mul_f32 v[124:125], v[112:113], v[136:137] op_sel_hi:[1,0]
	v_pk_mul_f32 v[122:123], v[114:115], v[136:137] op_sel_hi:[1,0]
	v_or_b32_e32 v120, s89, v138
	s_cbranch_scc1 .LBB0_164
	s_cmp_lt_i32 s88, 16
	s_cbranch_scc1 .LBB0_165
	s_cmp_gt_i32 s88, 17
	s_mov_b64 s[6:7], -1
	s_cselect_b64 s[56:57], -1, 0
	s_cbranch_execz .LBB0_166
	s_branch .LBB0_167
